# branch-projection items in feature-tile-fastest order (8 concurrent tiles of an XCD share each Y tile in L2)
# speedup vs baseline: 1.0059x; 1.0022x over previous
; #define OPQ int tid = tid0; asm volatile("" : "+v"(tid));
; template <int WT>
; DEV void branch_item(const Params& p, int l, int t0, int tf, char* smem, int tid) {
;   const int f0 = tf * 128;
;   const int wid = tid >> 6, lane = tid & 63, fr = lane & 15, fq = lane >> 4, wn = wid & 3, wt = wid >> 2;
;   f32x4 mg[2][WT];
;   zero_acc<2, WT>(mg);
; #pragma nounroll
;   for (int br = 0; br < 3; ++br) {
;     f32x4 acc[2][WT];
;     zero_acc<2, WT>(acc);
;     constexpr bool PREG = (WT <= 6);
;     uint2 gzr[2][PREG ? WT : 1];
;     if (PREG) {
; #pragma unroll
;       for (int n = 0; n < 2; ++n)
; #pragma unroll
;         for (int t = 0; t < (PREG ? WT : 1); ++t)
;           gzr[n][t] = *(const uint2*)(p.z + (long)(t0 + wt * (WT * 16) + t * 16 + fr) * NINP + C_BRG + br * 1024 + f0 + wn * 32 + n * 16 + fq * 4);
;     }
;     gemm_mainloop<2, WT>(p.WbrT + ((long)(l * 3 + br) * 1024 + f0) * 512, 512, p.Y + ((long)br * TG + t0) * 512, 512, 512, smem, tid, acc);
; __global__ void __launch_bounds__(512) mega(Params p, int coop) {
;     ...
;           for (int j = xr; j < 96; j += xper) { OPQ branch_item<6>(p, l, (xx * 12 + j % 12) * 192, j / 12, smem, tid); }
.LBB0_1181:
	s_and_b32 s6, s15, 7
	s_ashr_i32 s7, s15, 3
	v_readlane_b32 s8, v255, 10
	v_mov_b32_e32 v22, v197
	s_add_i32 s7, s7, s8
	s_mul_i32 s8, s7, 0xc0
	v_and_b32_e32 v10, 15, v22
	v_lshrrev_b32_e32 v0, 8, v22
	v_or_b32_e32 v1, s8, v10
	s_movk_i32 s7, 0x60
	v_mul_i32_i24_e32 v11, 0x60, v0
	v_mad_i32_i24 v48, v0, s7, v1
	v_lshrrev_b32_e32 v0, 1, v22
	v_and_b32_e32 v166, 0x60, v0
	v_add_u32_e32 v8, 0x200, v22
	v_add_u32_e32 v12, 0x400, v22
	v_lshrrev_b32_e32 v23, 4, v22
	v_bfe_u32 v24, v22, 4, 2
	v_ashrrev_i32_e32 v4, 3, v8
	v_lshlrev_b32_e32 v169, 4, v8
	v_ashrrev_i32_e32 v8, 3, v12
	v_lshlrev_b32_e32 v170, 4, v12
	v_or_b32_e32 v12, v166, v10
	v_bfe_u32 v13, v22, 1, 3
	v_or_b32_e32 v10, v11, v10
	v_bitop3_b32 v11, v23, v13, 3 bitop3:0x6c
	v_lshlrev_b32_e32 v173, 7, v10
	v_bitop3_b32 v10, v24, v13, 4 bitop3:0x36
	s_lshl_b32 s6, s6, 7
	v_lshlrev_b32_e32 v171, 4, v11
	v_lshlrev_b32_e32 v174, 4, v10
	v_mov_b64_e32 v[10:11], s[88:89]
	s_ashr_i32 s7, s6, 31
	v_lshlrev_b32_e32 v172, 7, v12
	v_or_b32_e32 v58, 16, v48
	v_add_u32_e32 v56, 32, v48
	v_add_u32_e32 v54, 48, v48
	v_add_u32_e32 v52, 64, v48
	v_add_u32_e32 v50, 0x50, v48
	v_mad_i64_i32 v[12:13], s[12:13], v48, s33, v[10:11]
	s_lshl_b64 s[12:13], s[6:7], 1
	v_mad_i64_i32 v[14:15], s[16:17], v58, s33, v[10:11]
	v_mad_i64_i32 v[16:17], s[16:17], v56, s33, v[10:11]
	v_mad_i64_i32 v[18:19], s[16:17], v54, s33, v[10:11]
	v_mad_i64_i32 v[20:21], s[16:17], v52, s33, v[10:11]
	v_mad_i64_i32 v[10:11], s[16:17], v50, s33, v[10:11]
	v_lshl_add_u64 v[12:13], v[12:13], 0, s[12:13]
	v_lshlrev_b32_e32 v156, 1, v166
	v_lshl_add_u64 v[14:15], v[14:15], 0, s[12:13]
	v_lshl_add_u64 v[16:17], v[16:17], 0, s[12:13]
	v_lshl_add_u64 v[18:19], v[18:19], 0, s[12:13]
	v_lshl_add_u64 v[20:21], v[20:21], 0, s[12:13]
	v_lshl_add_u64 v[10:11], v[10:11], 0, s[12:13]
	v_lshl_add_u64 v[12:13], v[12:13], 0, v[156:157]
	v_lshl_add_u64 v[14:15], v[14:15], 0, v[156:157]
	v_lshl_add_u64 v[16:17], v[16:17], 0, v[156:157]
	v_lshl_add_u64 v[18:19], v[18:19], 0, v[156:157]
	v_lshl_add_u64 v[20:21], v[20:21], 0, v[156:157]
	v_lshl_add_u64 v[10:11], v[10:11], 0, v[156:157]
	v_lshlrev_b32_e32 v156, 3, v24
	v_lshl_add_u64 v[12:13], v[12:13], 0, v[156:157]
	s_mov_b64 s[16:17], 0x2b40
	v_readlane_b32 s44, v253, 7
	v_lshl_add_u64 v[62:63], v[12:13], 0, s[16:17]
	v_lshl_add_u64 v[12:13], v[14:15], 0, v[156:157]
	s_lshl_b64 s[10:11], s[6:7], 10
	s_ashr_i32 s9, s8, 31
	v_xor_b32_e32 v25, v23, v22
	v_readlane_b32 s54, v253, 17
	v_lshl_add_u64 v[64:65], v[12:13], 0, s[16:17]
	v_lshl_add_u64 v[12:13], v[16:17], 0, v[156:157]
	v_lshl_add_u64 v[10:11], v[10:11], 0, v[156:157]
	v_readlane_b32 s55, v253, 18
	s_add_u32 s12, s54, s10
	v_lshl_add_u64 v[66:67], v[12:13], 0, s[16:17]
	v_lshl_add_u64 v[12:13], v[18:19], 0, v[156:157]
	v_lshl_add_u64 v[72:73], v[10:11], 0, s[16:17]
	v_lshlrev_b32_e32 v10, 4, v25
	v_ashrrev_i32_e32 v9, 31, v8
	s_addc_u32 s13, s55, s11
	v_lshl_add_u64 v[68:69], v[12:13], 0, s[16:17]
	v_lshl_add_u64 v[12:13], v[20:21], 0, v[156:157]
	v_and_b32_e32 v156, 0x70, v10
	v_lshlrev_b64 v[60:61], 9, v[8:9]
	v_lshl_add_u64 v[74:75], s[12:13], 0, v[156:157]
	v_lshlrev_b64 v[8:9], 10, v[8:9]
	s_lshl_b64 s[12:13], s[8:9], 10
	v_bitop3_b32 v10, v23, 7, v22 bitop3:0x48
	v_ashrrev_i32_e32 v5, 31, v4
	v_lshl_add_u64 v[70:71], v[12:13], 0, s[16:17]
	v_lshl_add_u64 v[8:9], v[8:9], 0, s[12:13]
	v_lshlrev_b32_e32 v10, 4, v10
	v_readlane_b32 s16, v254, 51
	v_ashrrev_i32_e32 v0, 3, v22
	v_lshlrev_b64 v[6:7], 9, v[4:5]
	v_or_b32_e32 v8, v8, v10
	v_readlane_b32 s17, v254, 52
	v_lshlrev_b64 v[4:5], 10, v[4:5]
	v_ashrrev_i32_e32 v1, 31, v0
	v_lshl_add_u64 v[88:89], s[16:17], 0, v[8:9]
	v_lshl_add_u64 v[8:9], v[4:5], 0, s[12:13]
	v_lshlrev_b64 v[2:3], 9, v[0:1]
	v_or_b32_e32 v8, v8, v10
	v_lshlrev_b64 v[0:1], 10, v[0:1]
	v_lshl_add_u64 v[104:105], s[16:17], 0, v[8:9]
	v_lshl_add_u64 v[8:9], v[0:1], 0, s[12:13]
	v_lshl_add_u64 v[4:5], v[4:5], 0, s[10:11]
	v_readlane_b32 s12, v255, 32
	v_lshl_add_u64 v[0:1], v[0:1], 0, s[10:11]
	v_lshl_add_u64 v[76:77], s[60:61], 0, v[156:157]
	v_or_b32_e32 v8, v8, v10
	v_or_b32_e32 v4, v4, v10
	v_readlane_b32 s13, v255, 33
	v_or_b32_e32 v0, v0, v10
	v_mov_b32_e32 v156, 0
	v_lshlrev_b32_e32 v167, 2, v24
	v_lshlrev_b32_e32 v168, 4, v22
	v_ashrrev_i32_e32 v49, 31, v48
	v_ashrrev_i32_e32 v59, 31, v58
	v_ashrrev_i32_e32 v57, 31, v56
	v_ashrrev_i32_e32 v55, 31, v54
	v_ashrrev_i32_e32 v53, 31, v52
	v_ashrrev_i32_e32 v51, 31, v50
	v_lshl_add_u64 v[114:115], s[16:17], 0, v[8:9]
	v_lshl_add_u64 v[124:125], s[12:13], 0, v[4:5]
	v_lshl_add_u64 v[130:131], s[12:13], 0, v[0:1]
	s_mov_b32 s7, 0
	v_lshlrev_b64 v[132:133], 1, v[2:3]
	v_lshlrev_b64 v[134:135], 1, v[6:7]
	v_mov_b32_e32 v136, 0
	v_mov_b32_e32 v137, v156
	v_mov_b32_e32 v138, 0
	v_mov_b32_e32 v139, v156
	v_mov_b32_e32 v126, 0
	v_mov_b32_e32 v127, v156
	v_mov_b32_e32 v128, 0
	v_mov_b32_e32 v129, v156
	v_mov_b32_e32 v120, 0
	v_mov_b32_e32 v121, v156
	v_mov_b32_e32 v122, 0
	v_mov_b32_e32 v123, v156
	v_mov_b32_e32 v116, 0
	v_mov_b32_e32 v117, v156
	v_mov_b32_e32 v118, 0
	v_mov_b32_e32 v119, v156
	v_mov_b32_e32 v110, 0
	v_mov_b32_e32 v111, v156
	v_mov_b32_e32 v112, 0
	v_mov_b32_e32 v113, v156
	v_mov_b32_e32 v106, 0
	v_mov_b32_e32 v107, v156
	v_mov_b32_e32 v108, 0
	v_mov_b32_e32 v109, v156
	v_mov_b32_e32 v98, 0
	v_mov_b32_e32 v99, v156
	v_mov_b32_e32 v102, 0
	v_mov_b32_e32 v103, v156
	v_mov_b32_e32 v94, 0
	v_mov_b32_e32 v95, v156
	v_mov_b32_e32 v100, 0
	v_mov_b32_e32 v101, v156
	v_mov_b32_e32 v90, 0
	v_mov_b32_e32 v91, v156
	v_mov_b32_e32 v96, 0
	v_mov_b32_e32 v97, v156
	v_mov_b32_e32 v84, 0
	v_mov_b32_e32 v85, v156
	v_mov_b32_e32 v92, 0
	v_mov_b32_e32 v93, v156
	v_mov_b32_e32 v80, 0
	v_mov_b32_e32 v81, v156
	v_mov_b32_e32 v86, 0
	v_mov_b32_e32 v87, v156
	v_mov_b32_e32 v78, 0
	v_mov_b32_e32 v79, v156
	v_mov_b32_e32 v82, 0
	v_mov_b32_e32 v83, v156
	v_readlane_b32 s45, v253, 8
	v_readlane_b32 s46, v253, 9
	v_readlane_b32 s47, v253, 10
	v_readlane_b32 s48, v253, 11
	v_readlane_b32 s49, v253, 12
	v_readlane_b32 s50, v253, 13
	v_readlane_b32 s51, v253, 14
	v_readlane_b32 s52, v253, 15
	v_readlane_b32 s53, v253, 16
	v_readlane_b32 s56, v253, 19
	v_readlane_b32 s57, v253, 20
	v_readlane_b32 s58, v253, 21
	v_readlane_b32 s59, v253, 22
	s_branch .LBB0_1183
